# mLSTM conv rows: prev/next token rows loaded together with the centre row; mlstm_out touches V/gate/C_start lines early
# baseline (speedup 1.0000x reference)
; __device__ __forceinline__ uint4 conv8_bf(const bf16_t* zr, int c, bool hp, bool hn, const float* cw, const float* cb, float scale) {
;     const bf16x8 cur = *(const bf16x8*)(zr + c);
;     bf16x8 pv = cur, nx = cur;
;     if (hp) pv = *(const bf16x8*)(zr + c - 784);
;     if (hn) nx = *(const bf16x8*)(zr + c + 784);
; __device__ __forceinline__ void mlstm_out_unit(const Params& p, int layer, int uci, char* smem) {
;     ...
;     const int ci = uci % 68, bhd = uci / 68, b = bhd >> 3, h = (bhd >> 1) & 3, d = bhd & 1;
;     float* F = (float*)(smem + MO_F);
;     __syncthreads();
;     float* slot = (float*)(p.ws + OFF_HM) + (size_t)uci * 2048;
;     const float* mls = (const float*)(p.ws + OFF_MLS2) + (size_t)uci * 36;
;     const float mst = mls[33];
;     {
;         const bf16_t* zm = (const bf16_t*)(p.ws + OFF_ZM);
;         const float* cw = p.in[29] + (size_t)layer * 3 * 256; const float* cb = p.in[30] + (size_t)layer * 256;
;         const int s = tid >> 2, part = tid & 3;
;         const int t = step_tok(ci * 64 + s, d);
;         const int lo = t < CTX ? 0 : CTX, hi = t < CTX ? CTX : TT;
;         const bool hp = t > lo, hn = t + 1 < hi;
;         const bf16_t* zr = zm + ((size_t)b * TT + t) * 784;
;         if (part < 2) { const int kc = part * 16;
;             *(uint4*)(smem + MO_Q + s * 80 + kc * 2) = conv8_bf(zr, h * 32 + kc, hp, hn, cw, cb, 0.17677669529663687f);
;             *(uint4*)(smem + MO_Q + s * 80 + kc * 2 + 16) = conv8_bf(zr, h * 32 + kc + 8, hp, hn, cw, cb, 0.17677669529663687f); }
;         else { const int kc = (part - 2) * 16;
;             *(uint4*)(smem + MO_K + s * 80 + kc * 2) = conv8_bf(zr, 128 + h * 32 + kc, hp, hn, cw, cb, 1.f);
;             *(uint4*)(smem + MO_K + s * 80 + kc * 2 + 16) = conv8_bf(zr, 128 + h * 32 + kc + 8, hp, hn, cw, cb, 1.f); }
;         {
;             const bf16x8 v0 = *(const bf16x8*)(zr + 256 + h * 64 + part * 16), v1 = *(const bf16x8*)(zr + 256 + h * 64 + part * 16 + 8);
.Lpf3_skipb:
	s_mov_b64 exec, s[98:99]
	s_mul_hi_i32 s1, s0, 0x78787879
	s_lshr_b32 s30, s1, 31
	s_ashr_i32 s1, s1, 5
	s_add_i32 s30, s1, s30
	s_mul_i32 s1, s30, 0x44
	s_sub_i32 s1, s0, s1
	s_cmp_lt_i32 s1, 4
	s_cselect_b64 s[34:35], -1, 0
	s_and_b64 s[34:35], s[12:13], s[34:35]
	s_and_b64 vcc, exec, s[34:35]
	s_cbranch_vccnz .LBB0_470
	s_ashr_i32 s31, s30, 3
	s_bfe_u32 s50, s30, 0x20001
	s_and_b32 s51, s30, 1
	s_mul_i32 s34, s0, 0x90
	v_readlane_b32 s4, v251, 52
	s_mul_hi_i32 s30, s0, 0x90
	s_add_u32 s48, s4, s34
	v_readlane_b32 s4, v251, 53
	s_waitcnt vmcnt(11)
	v_mov_b32_e32 v28, v109
	s_addc_u32 s49, s4, s30
	s_barrier
	global_load_dword v40, v105, s[48:49] offset:132
	v_ashrrev_i32_e32 v31, 2, v28
	v_lshl_add_u32 v0, s1, 6, v31
	v_cmp_lt_i32_e32 vcc, s2, v0
	s_cmp_eq_u32 s51, 0
	s_movk_i32 s1, 0x100
	v_cndmask_b32_e32 v1, v196, v197, vcc
	v_sub_u32_e32 v1, v1, v0
	s_cselect_b64 vcc, -1, 0
	v_cndmask_b32_e32 v0, v1, v0, vcc
	v_cmp_gt_i32_e32 vcc, s1, v0
	v_readlane_b32 s4, v252, 2
	v_readlane_b32 s5, v252, 3
	v_cndmask_b32_e64 v1, v205, 0, vcc
	v_cndmask_b32_e32 v2, v204, v205, vcc
	v_cmp_gt_i32_e64 s[46:47], v0, v1
	v_add_u32_e32 v1, 1, v0
	v_cmp_lt_i32_e64 s[44:45], v1, v2
	v_ashrrev_i32_e32 v1, 31, v0
	v_mad_i64_i32 v[0:1], s[30:31], s31, v204, v[0:1]
	v_mov_b64_e32 v[2:3], s[4:5]
	s_movk_i32 s1, 0x620
	v_and_b32_e32 v29, 3, v28
	s_waitcnt vmcnt(10)
	v_mad_u64_u32 v[32:33], s[30:31], v0, s1, v[2:3]
	v_mad_i32_i24 v33, v1, s1, v33
	s_lshl_b32 s98, s50, 7
	s_mov_b32 s99, 0
	global_load_dword v237, v[32:33], off offset:1536
	v_lshl_add_u64 v[238:239], v[32:33], 0, s[98:99]
	v_lshlrev_b32_e32 v236, 5, v109
	global_load_dword v237, v[238:239], off offset:512
	v_readlane_b32 s98, v251, 42
	v_readlane_b32 s99, v251, 43
	v_lshl_add_u32 v236, s0, 13, v236
	s_nop 4
	global_load_dword v237, v236, s[98:99]
	v_cmp_lt_u32_e64 s[100:101], 1, v29
	v_lshlrev_b32_e32 v30, 4, v29
	s_mov_b64 vcc, exec
	s_and_saveexec_b64 s[30:31], vcc
	s_xor_b64 s[34:35], exec, s[30:31]
	v_mov_b32_e32 v224, 0xffffff00
	v_mov_b32_e32 v226, 0xfffffe00
	v_mov_b32_e32 v228, 0x3e3504f3
	v_mov_b32_e32 v230, 0x1400
	v_cndmask_b32_e64 v224, v224, 0, s[100:101]
	v_cndmask_b32_e64 v225, -1, 0, s[100:101]
	v_cndmask_b32_e64 v226, v226, 0, s[100:101]
	v_cndmask_b32_e64 v228, v228, 1.0, s[100:101]
	v_cndmask_b32_e64 v230, 0, v230, s[100:101]
	v_mov_b32_e32 v227, v225
	v_mov_b32_e32 v229, v228
	s_cbranch_execz .LBB0_494
	s_waitcnt vmcnt(9)
	v_and_b32_e32 v41, 16, v30
	v_lshl_add_u32 v104, s50, 5, v41
	v_lshl_add_u64 v[34:35], v[104:105], 1, v[32:33]
	v_lshl_add_u64 v[34:35], v[34:35], 0, v[224:225]
	global_load_dwordx4 v[4:7], v[34:35], off offset:256
	global_load_dwordx4 v[0:3], v[34:35], off offset:-1312
	global_load_dwordx4 v[8:11], v[34:35], off offset:1824
	v_readlane_b32 s4, v254, 44
	v_lshlrev_b64 v[24:25], 2, v[104:105]
	v_lshl_add_u64 v[24:25], v[24:25], 0, v[226:227]
	v_readlane_b32 s5, v254, 45
	v_lshl_add_u64 v[36:37], s[4:5], 0, v[24:25]
	v_readlane_b32 s4, v254, 46
	v_readlane_b32 s5, v254, 47
	global_load_dwordx4 v[16:19], v[36:37], off offset:528
	global_load_dwordx4 v[42:45], v[36:37], off offset:512
	global_load_dwordx4 v[20:23], v[36:37], off offset:1552
	global_load_dwordx4 v[46:49], v[36:37], off offset:1536
	global_load_dwordx4 v[12:15], v[36:37], off offset:2576
	global_load_dwordx4 v[50:53], v[36:37], off offset:2560
	v_lshl_add_u64 v[38:39], s[4:5], 0, v[24:25]
	global_load_dwordx4 v[24:27], v[38:39], off offset:528
	global_load_dwordx4 v[54:57], v[38:39], off offset:512
	s_waitcnt vmcnt(8)
	v_and_b32_e32 v63, 0xffff0000, v4
	v_lshlrev_b32_e32 v62, 16, v4
	v_and_b32_e32 v61, 0xffff0000, v0
	v_lshlrev_b32_e32 v60, 16, v0
	v_and_b32_e32 v59, 0xffff0000, v8
	v_lshlrev_b32_e32 v58, 16, v8
	s_movk_i32 s1, 0x50
	s_waitcnt vmcnt(0)
	v_pk_fma_f32 v[46:47], v[46:47], v[62:63], v[54:55]
	s_nop 0
	v_pk_fma_f32 v[42:43], v[42:43], v[60:61], v[46:47]
	s_nop 0
	v_cndmask_b32_e64 v43, v47, v43, s[46:47]
	v_cndmask_b32_e64 v42, v46, v42, s[46:47]
	v_pk_fma_f32 v[46:47], v[50:51], v[58:59], v[42:43]
	s_nop 0
	v_cndmask_b32_e64 v4, v42, v46, s[44:45]
	v_cndmask_b32_e64 v0, v43, v47, s[44:45]
	v_mul_f32_e32 v8, 0xbfb8aa3b, v4
	v_exp_f32_e32 v42, v8
	v_mul_f32_e32 v8, 0xbfb8aa3b, v0
	v_exp_f32_e32 v43, v8
	s_nop 0
	v_pk_add_f32 v[42:43], v[42:43], 1.0 op_sel_hi:[1,0]
	s_nop 0
	v_div_scale_f32 v8, s[30:31], v43, v43, v0
	v_rcp_f32_e32 v46, v8
	s_nop 0
	v_fma_f32 v47, -v8, v46, 1.0
	v_fmac_f32_e32 v46, v47, v46
	v_div_scale_f32 v47, vcc, v0, v43, v0
	v_mul_f32_e32 v50, v47, v46
	v_fma_f32 v51, -v8, v50, v47
	v_fmac_f32_e32 v50, v51, v46
	v_fma_f32 v8, -v8, v50, v47
	v_div_fmas_f32 v8, v8, v46, v50
	v_div_fixup_f32 v0, v8, v43, v0
	v_div_scale_f32 v8, s[30:31], v42, v42, v4
	v_rcp_f32_e32 v43, v8
	s_nop 0
	v_fma_f32 v46, -v8, v43, 1.0
	v_fmac_f32_e32 v43, v46, v43
	v_div_scale_f32 v46, vcc, v4, v42, v4
	v_mul_f32_e32 v47, v46, v43
	v_fma_f32 v50, -v8, v47, v46
	v_fmac_f32_e32 v47, v50, v43
	v_fma_f32 v8, -v8, v47, v46
	v_div_fmas_f32 v8, v8, v43, v47
	v_and_b32_e32 v47, 0xffff0000, v5
	v_lshlrev_b32_e32 v46, 16, v5
	v_div_fixup_f32 v4, v8, v42, v4
	v_and_b32_e32 v43, 0xffff0000, v9
	v_lshlrev_b32_e32 v42, 16, v9
	v_and_b32_e32 v9, 0xffff0000, v1
	v_lshlrev_b32_e32 v8, 16, v1
	v_pk_fma_f32 v[46:47], v[48:49], v[46:47], v[56:57]
	v_mul_f32_e32 v231, v228, v4
	v_mul_f32_e32 v232, v228, v0
	v_cvt_pk_bf16_f32 v0, v231, v232
	v_pk_fma_f32 v[8:9], v[44:45], v[8:9], v[46:47]
	v_mul_lo_u32 v4, v31, s1
	v_cndmask_b32_e64 v9, v47, v9, s[46:47]
	v_cndmask_b32_e64 v8, v46, v8, s[46:47]
	v_pk_fma_f32 v[42:43], v[52:53], v[42:43], v[8:9]
	s_nop 0
	v_cndmask_b32_e64 v1, v9, v43, s[44:45]
; __device__ __forceinline__ float bf2f(bf16_t h) { return __uint_as_float(((unsigned)h) << 16); }
; __device__ __forceinline__ unsigned pack2bf(float a, float b) { const f32x2 v = {a, b}; return __builtin_bit_cast(unsigned, __builtin_convertvector(v, bf2_t)); }
; __device__ __forceinline__ float siluf_(float x) { return x / (1.f + __expf(-x)); }
; __device__ __forceinline__ uint4 conv8_bf(const bf16_t* zr, int c, bool hp, bool hn, const float* cw, const float* cb, float scale) {
;     ...
;     for (int j = 0; j < 8; ++j) {
;         const float w0 = j < 4 ? w0a[j & 3] : w0b[j & 3], w1 = j < 4 ? w1a[j & 3] : w1b[j & 3], w2 = j < 4 ? w2a[j & 3] : w2b[j & 3], bb = j < 4 ? bba[j & 3] : bbb[j & 3];
;         float a = bf2f((bf16_t)cur[j]) * w1 + bb;
;         if (hp) a += bf2f((bf16_t)pv[j]) * w0;
;         if (hn) a += bf2f((bf16_t)nx[j]) * w2;
;         o[j] = siluf_(a) * scale;
;     }
;     uint4 w; w.x = pack2bf(o[0], o[1]); w.y = pack2bf(o[2], o[3]); w.z = pack2bf(o[4], o[5]); w.w = pack2bf(o[6], o[7]);
; __device__ __forceinline__ void mlstm_out_unit(const Params& p, int layer, int uci, char* smem) {
;     ...
;         if (part < 2) { const int kc = part * 16;
;             *(uint4*)(smem + MO_Q + s * 80 + kc * 2) = conv8_bf(zr, h * 32 + kc, hp, hn, cw, cb, 0.17677669529663687f);
;             *(uint4*)(smem + MO_Q + s * 80 + kc * 2 + 16) = conv8_bf(zr, h * 32 + kc + 8, hp, hn, cw, cb, 0.17677669529663687f); }
;         else { const int kc = (part - 2) * 16;
;             *(uint4*)(smem + MO_K + s * 80 + kc * 2) = conv8_bf(zr, 128 + h * 32 + kc, hp, hn, cw, cb, 1.f);
;             *(uint4*)(smem + MO_K + s * 80 + kc * 2 + 16) = conv8_bf(zr, 128 + h * 32 + kc + 8, hp, hn, cw, cb, 1.f); }
	v_cndmask_b32_e64 v5, v8, v42, s[44:45]
	v_mul_f32_e32 v8, 0xbfb8aa3b, v5
	v_mul_f32_e32 v9, 0xbfb8aa3b, v1
	v_exp_f32_e32 v8, v8
	v_exp_f32_e32 v9, v9
	s_nop 0
	v_pk_add_f32 v[8:9], v[8:9], 1.0 op_sel_hi:[1,0]
	s_nop 0
	v_div_scale_f32 v42, s[30:31], v9, v9, v1
	v_rcp_f32_e32 v43, v42
	s_nop 0
	v_fma_f32 v44, -v42, v43, 1.0
	v_fmac_f32_e32 v43, v44, v43
	v_div_scale_f32 v44, vcc, v1, v9, v1
	v_mul_f32_e32 v45, v44, v43
	v_fma_f32 v46, -v42, v45, v44
	v_fmac_f32_e32 v45, v46, v43
	v_fma_f32 v42, -v42, v45, v44
	v_div_fmas_f32 v42, v42, v43, v45
	v_div_fixup_f32 v1, v42, v9, v1
	v_div_scale_f32 v9, s[30:31], v8, v8, v5
	v_rcp_f32_e32 v42, v9
	s_nop 0
	v_fma_f32 v43, -v9, v42, 1.0
	v_fmac_f32_e32 v42, v43, v42
	v_div_scale_f32 v43, vcc, v5, v8, v5
	v_mul_f32_e32 v44, v43, v42
	v_fma_f32 v45, -v9, v44, v43
	v_fmac_f32_e32 v44, v45, v42
	v_fma_f32 v9, -v9, v44, v43
	v_div_fmas_f32 v9, v9, v42, v44
	v_and_b32_e32 v45, 0xffff0000, v6
	v_lshlrev_b32_e32 v44, 16, v6
	v_and_b32_e32 v43, 0xffff0000, v2
	v_lshlrev_b32_e32 v42, 16, v2
	v_pk_fma_f32 v[20:21], v[20:21], v[44:45], v[24:25]
	v_div_fixup_f32 v5, v9, v8, v5
	v_pk_fma_f32 v[16:17], v[16:17], v[42:43], v[20:21]
	v_and_b32_e32 v9, 0xffff0000, v10
	v_lshlrev_b32_e32 v8, 16, v10
	v_cndmask_b32_e64 v17, v21, v17, s[46:47]
	v_cndmask_b32_e64 v16, v20, v16, s[46:47]
	v_pk_fma_f32 v[8:9], v[12:13], v[8:9], v[16:17]
	v_mul_f32_e32 v231, v228, v5
	v_mul_f32_e32 v232, v228, v1
	v_cvt_pk_bf16_f32 v1, v231, v232
	v_cndmask_b32_e64 v2, v17, v9, s[44:45]
	v_cndmask_b32_e64 v6, v16, v8, s[44:45]
	v_mul_f32_e32 v8, 0xbfb8aa3b, v6
	v_mul_f32_e32 v9, 0xbfb8aa3b, v2
	v_exp_f32_e32 v8, v8
	v_exp_f32_e32 v9, v9
	s_nop 0
	v_pk_add_f32 v[8:9], v[8:9], 1.0 op_sel_hi:[1,0]
	s_nop 0
	v_div_scale_f32 v10, s[30:31], v9, v9, v2
	v_rcp_f32_e32 v12, v10
	s_nop 0
	v_fma_f32 v13, -v10, v12, 1.0
	v_fmac_f32_e32 v12, v13, v12
	v_div_scale_f32 v13, vcc, v2, v9, v2
	v_mul_f32_e32 v16, v13, v12
	v_fma_f32 v17, -v10, v16, v13
	v_fmac_f32_e32 v16, v17, v12
	v_fma_f32 v10, -v10, v16, v13
	v_div_fmas_f32 v10, v10, v12, v16
	v_div_fixup_f32 v10, v10, v9, v2
	v_div_scale_f32 v2, s[30:31], v8, v8, v6
	v_rcp_f32_e32 v9, v2
	s_nop 0
	v_fma_f32 v12, -v2, v9, 1.0
	v_fmac_f32_e32 v9, v12, v9
	v_div_scale_f32 v12, vcc, v6, v8, v6
	v_mul_f32_e32 v13, v12, v9
	v_fma_f32 v16, -v2, v13, v12
	v_fmac_f32_e32 v13, v16, v9
	v_fma_f32 v2, -v2, v13, v12
	v_div_fmas_f32 v2, v2, v9, v13
	v_div_fixup_f32 v12, v2, v8, v6
	v_and_b32_e32 v9, 0xffff0000, v7
	v_lshlrev_b32_e32 v8, 16, v7
	v_pk_fma_f32 v[6:7], v[22:23], v[8:9], v[26:27]
	v_and_b32_e32 v9, 0xffff0000, v3
	v_lshlrev_b32_e32 v8, 16, v3
	v_pk_fma_f32 v[2:3], v[18:19], v[8:9], v[6:7]
	s_nop 0
	v_cndmask_b32_e64 v3, v7, v3, s[46:47]
	v_cndmask_b32_e64 v2, v6, v2, s[46:47]
	v_and_b32_e32 v7, 0xffff0000, v11
	v_lshlrev_b32_e32 v6, 16, v11
	v_pk_fma_f32 v[6:7], v[14:15], v[6:7], v[2:3]
	s_nop 0
	v_cndmask_b32_e64 v7, v3, v7, s[44:45]
	v_cndmask_b32_e64 v6, v2, v6, s[44:45]
	v_mul_f32_e32 v2, 0xbfb8aa3b, v6
	v_mul_f32_e32 v3, 0xbfb8aa3b, v7
	v_exp_f32_e32 v2, v2
	v_exp_f32_e32 v3, v3
	s_nop 0
	v_pk_add_f32 v[2:3], v[2:3], 1.0 op_sel_hi:[1,0]
	s_nop 0
	v_div_scale_f32 v8, s[30:31], v3, v3, v7
	v_rcp_f32_e32 v9, v8
	s_nop 0
	v_fma_f32 v11, -v8, v9, 1.0
	v_fmac_f32_e32 v9, v11, v9
	v_div_scale_f32 v11, vcc, v7, v3, v7
	v_mul_f32_e32 v13, v11, v9
	v_fma_f32 v14, -v8, v13, v11
	v_fmac_f32_e32 v13, v14, v9
	v_fma_f32 v8, -v8, v13, v11
	v_div_fmas_f32 v8, v8, v9, v13
	v_div_fixup_f32 v3, v8, v3, v7
	v_div_scale_f32 v7, s[30:31], v2, v2, v6
	v_rcp_f32_e32 v8, v7
	s_nop 0
	v_fma_f32 v9, -v7, v8, 1.0
	v_fmac_f32_e32 v8, v9, v8
	v_div_scale_f32 v9, vcc, v6, v2, v6
	v_mul_f32_e32 v11, v9, v8
	v_fma_f32 v13, -v7, v11, v9
	v_fmac_f32_e32 v11, v13, v8
	v_fma_f32 v7, -v7, v11, v9
	v_div_fmas_f32 v7, v7, v8, v11
	v_div_fixup_f32 v6, v7, v2, v6
	v_mul_f32_e32 v231, v228, v12
	v_mul_f32_e32 v232, v228, v10
	v_cvt_pk_bf16_f32 v2, v231, v232
	v_mul_f32_e32 v231, v228, v6
	v_mul_f32_e32 v232, v228, v3
	v_cvt_pk_bf16_f32 v3, v231, v232
	v_lshl_add_u32 v12, v41, 1, v4
	v_add_u32_e32 v233, v230, v12
	ds_write_b128 v233, v[0:3]
	global_load_dwordx4 v[0:3], v[34:35], off offset:272
	global_load_dwordx4 v[4:7], v[34:35], off offset:-1296
	global_load_dwordx4 v[8:11], v[34:35], off offset:1840
	v_add_u32_e32 v41, v230, v12
	global_load_dwordx4 v[16:19], v[36:37], off offset:560
	global_load_dwordx4 v[42:45], v[36:37], off offset:544
	global_load_dwordx4 v[20:23], v[36:37], off offset:1584
	global_load_dwordx4 v[46:49], v[36:37], off offset:1568
	global_load_dwordx4 v[12:15], v[36:37], off offset:2608
	s_nop 0
	global_load_dwordx4 v[34:37], v[36:37], off offset:2592
	s_nop 0
	global_load_dwordx4 v[24:27], v[38:39], off offset:560
	global_load_dwordx4 v[50:53], v[38:39], off offset:544
	s_waitcnt vmcnt(8)
	v_and_b32_e32 v57, 0xffff0000, v0
	v_lshlrev_b32_e32 v56, 16, v0
	v_and_b32_e32 v55, 0xffff0000, v4
	v_lshlrev_b32_e32 v54, 16, v4
	v_and_b32_e32 v39, 0xffff0000, v8
	v_lshlrev_b32_e32 v38, 16, v8
	s_waitcnt vmcnt(0)
; __device__ __forceinline__ float bf2f(bf16_t h) { return __uint_as_float(((unsigned)h) << 16); }
; __device__ __forceinline__ float siluf_(float x) { return x / (1.f + __expf(-x)); }
; __device__ __forceinline__ uint4 conv8_bf(const bf16_t* zr, int c, bool hp, bool hn, const float* cw, const float* cb, float scale) {
;     ...
;     for (int j = 0; j < 8; ++j) {
;         const float w0 = j < 4 ? w0a[j & 3] : w0b[j & 3], w1 = j < 4 ? w1a[j & 3] : w1b[j & 3], w2 = j < 4 ? w2a[j & 3] : w2b[j & 3], bb = j < 4 ? bba[j & 3] : bbb[j & 3];
;         float a = bf2f((bf16_t)cur[j]) * w1 + bb;
;         if (hp) a += bf2f((bf16_t)pv[j]) * w0;
;         if (hn) a += bf2f((bf16_t)nx[j]) * w2;
;         o[j] = siluf_(a) * scale;
;     }
	v_pk_fma_f32 v[46:47], v[46:47], v[56:57], v[50:51]
	s_nop 0
	v_pk_fma_f32 v[42:43], v[42:43], v[54:55], v[46:47]
	s_nop 0
	v_cndmask_b32_e64 v43, v47, v43, s[46:47]
	v_cndmask_b32_e64 v42, v46, v42, s[46:47]
	v_pk_fma_f32 v[34:35], v[34:35], v[38:39], v[42:43]
	s_nop 0
	v_cndmask_b32_e64 v4, v42, v34, s[44:45]
	v_cndmask_b32_e64 v0, v43, v35, s[44:45]
	v_mul_f32_e32 v8, 0xbfb8aa3b, v4
	v_exp_f32_e32 v34, v8
	v_mul_f32_e32 v8, 0xbfb8aa3b, v0
	v_exp_f32_e32 v35, v8
	s_nop 0
	v_pk_add_f32 v[34:35], v[34:35], 1.0 op_sel_hi:[1,0]
	s_nop 0
	v_div_scale_f32 v8, s[30:31], v35, v35, v0
	v_rcp_f32_e32 v38, v8
	s_nop 0
	v_fma_f32 v39, -v8, v38, 1.0
	v_fmac_f32_e32 v38, v39, v38
	v_div_scale_f32 v39, vcc, v0, v35, v0
	v_mul_f32_e32 v42, v39, v38
	v_fma_f32 v43, -v8, v42, v39
	v_fmac_f32_e32 v42, v43, v38
	v_fma_f32 v8, -v8, v42, v39
	v_div_fmas_f32 v8, v8, v38, v42
	v_div_fixup_f32 v35, v8, v35, v0
	v_div_scale_f32 v0, s[30:31], v34, v34, v4
	v_rcp_f32_e32 v8, v0
	s_nop 0
	v_fma_f32 v38, -v0, v8, 1.0
	v_fmac_f32_e32 v8, v38, v8
	v_div_scale_f32 v38, vcc, v4, v34, v4
	v_mul_f32_e32 v39, v38, v8
	v_fma_f32 v42, -v0, v39, v38
	v_fmac_f32_e32 v39, v42, v8
	v_fma_f32 v0, -v0, v39, v38
	v_div_fmas_f32 v0, v0, v8, v39
	v_div_fixup_f32 v34, v0, v34, v4
	v_and_b32_e32 v39, 0xffff0000, v9
	v_lshlrev_b32_e32 v38, 16, v9
	v_and_b32_e32 v9, 0xffff0000, v5
	v_lshlrev_b32_e32 v8, 16, v5
	v_and_b32_e32 v5, 0xffff0000, v1
	v_lshlrev_b32_e32 v4, 16, v1
	v_pk_fma_f32 v[0:1], v[48:49], v[4:5], v[52:53]
	s_nop 0
	v_pk_fma_f32 v[4:5], v[44:45], v[8:9], v[0:1]
	s_nop 0
	v_cndmask_b32_e64 v1, v1, v5, s[46:47]
	v_cndmask_b32_e64 v0, v0, v4, s[46:47]
	v_pk_fma_f32 v[4:5], v[36:37], v[38:39], v[0:1]
	s_nop 0
	v_cndmask_b32_e64 v5, v1, v5, s[44:45]
	v_cndmask_b32_e64 v4, v0, v4, s[44:45]
	v_mul_f32_e32 v0, 0xbfb8aa3b, v4
	v_mul_f32_e32 v1, 0xbfb8aa3b, v5
	v_exp_f32_e32 v0, v0
	v_exp_f32_e32 v1, v1
	s_nop 0
	v_pk_add_f32 v[0:1], v[0:1], 1.0 op_sel_hi:[1,0]
	s_nop 0
	v_div_scale_f32 v8, s[30:31], v1, v1, v5
	v_rcp_f32_e32 v9, v8
	s_nop 0
	v_fma_f32 v36, -v8, v9, 1.0
	v_fmac_f32_e32 v9, v36, v9
	v_div_scale_f32 v36, vcc, v5, v1, v5
	v_mul_f32_e32 v37, v36, v9
	v_fma_f32 v38, -v8, v37, v36
	v_fmac_f32_e32 v37, v38, v9
	v_fma_f32 v8, -v8, v37, v36
	v_div_fmas_f32 v8, v8, v9, v37
	v_div_fixup_f32 v1, v8, v1, v5
	v_div_scale_f32 v5, s[30:31], v0, v0, v4
	v_rcp_f32_e32 v8, v5
	s_nop 0
	v_fma_f32 v9, -v5, v8, 1.0
	v_fmac_f32_e32 v8, v9, v8
	v_div_scale_f32 v9, vcc, v4, v0, v4
	v_mul_f32_e32 v36, v9, v8
	v_fma_f32 v37, -v5, v36, v9
	v_fmac_f32_e32 v36, v37, v8
	v_fma_f32 v5, -v5, v36, v9
	v_div_fmas_f32 v5, v5, v8, v36
	v_and_b32_e32 v37, 0xffff0000, v2
	v_lshlrev_b32_e32 v36, 16, v2
	v_and_b32_e32 v9, 0xffff0000, v6
	v_lshlrev_b32_e32 v8, 16, v6
	v_pk_fma_f32 v[20:21], v[20:21], v[36:37], v[24:25]
	v_div_fixup_f32 v0, v5, v0, v4
	v_pk_fma_f32 v[8:9], v[16:17], v[8:9], v[20:21]
	v_and_b32_e32 v5, 0xffff0000, v10
	v_lshlrev_b32_e32 v4, 16, v10
	v_cndmask_b32_e64 v9, v21, v9, s[46:47]
	v_cndmask_b32_e64 v8, v20, v8, s[46:47]
	v_pk_fma_f32 v[4:5], v[12:13], v[4:5], v[8:9]
	s_nop 0
	v_cndmask_b32_e64 v2, v9, v5, s[44:45]
	v_cndmask_b32_e64 v6, v8, v4, s[44:45]
	v_mul_f32_e32 v4, 0xbfb8aa3b, v6
	v_mul_f32_e32 v5, 0xbfb8aa3b, v2
	v_exp_f32_e32 v4, v4
	v_exp_f32_e32 v5, v5
	s_nop 0
	v_pk_add_f32 v[4:5], v[4:5], 1.0 op_sel_hi:[1,0]
	s_nop 0
	v_div_scale_f32 v8, s[30:31], v5, v5, v2
	v_rcp_f32_e32 v9, v8
	s_nop 0
	v_fma_f32 v10, -v8, v9, 1.0
	v_fmac_f32_e32 v9, v10, v9
	v_div_scale_f32 v10, vcc, v2, v5, v2
	v_mul_f32_e32 v12, v10, v9
	v_fma_f32 v13, -v8, v12, v10
	v_fmac_f32_e32 v12, v13, v9
	v_fma_f32 v8, -v8, v12, v10
	v_div_fmas_f32 v8, v8, v9, v12
	v_div_fixup_f32 v5, v8, v5, v2
	v_div_scale_f32 v2, s[30:31], v4, v4, v6
	v_rcp_f32_e32 v8, v2
	s_nop 0
	v_fma_f32 v9, -v2, v8, 1.0
	v_fmac_f32_e32 v8, v9, v8
	v_div_scale_f32 v9, vcc, v6, v4, v6
	v_mul_f32_e32 v10, v9, v8
	v_fma_f32 v12, -v2, v10, v9
	v_fmac_f32_e32 v10, v12, v8
	v_fma_f32 v2, -v2, v10, v9
	v_div_fmas_f32 v2, v2, v8, v10
	v_and_b32_e32 v9, 0xffff0000, v3
	v_lshlrev_b32_e32 v8, 16, v3
	v_div_fixup_f32 v4, v2, v4, v6
	v_pk_fma_f32 v[2:3], v[22:23], v[8:9], v[26:27]
	v_and_b32_e32 v9, 0xffff0000, v7
	v_lshlrev_b32_e32 v8, 16, v7
	v_pk_fma_f32 v[6:7], v[18:19], v[8:9], v[2:3]
	s_nop 0
	v_cndmask_b32_e64 v3, v3, v7, s[46:47]
	v_cndmask_b32_e64 v2, v2, v6, s[46:47]
	v_and_b32_e32 v7, 0xffff0000, v11
	v_lshlrev_b32_e32 v6, 16, v11
	v_pk_fma_f32 v[6:7], v[14:15], v[6:7], v[2:3]
	s_nop 0
	v_cndmask_b32_e64 v7, v3, v7, s[44:45]
	v_cndmask_b32_e64 v6, v2, v6, s[44:45]
	v_mul_f32_e32 v2, 0xbfb8aa3b, v6
	v_mul_f32_e32 v3, 0xbfb8aa3b, v7
	v_exp_f32_e32 v2, v2
	v_exp_f32_e32 v3, v3
	s_nop 0
	v_pk_add_f32 v[2:3], v[2:3], 1.0 op_sel_hi:[1,0]
	s_nop 0
	v_div_scale_f32 v8, s[30:31], v3, v3, v7
	v_rcp_f32_e32 v9, v8
	s_nop 0
	v_fma_f32 v10, -v8, v9, 1.0
	v_fmac_f32_e32 v9, v10, v9
	v_div_scale_f32 v10, vcc, v7, v3, v7
	v_mul_f32_e32 v11, v10, v9
	v_fma_f32 v12, -v8, v11, v10
	v_fmac_f32_e32 v11, v12, v9
	v_fma_f32 v8, -v8, v11, v10
	v_div_fmas_f32 v8, v8, v9, v11
	v_div_fixup_f32 v3, v8, v3, v7
	v_div_scale_f32 v7, s[30:31], v2, v2, v6
	v_rcp_f32_e32 v8, v7
	s_nop 0
	v_fma_f32 v9, -v7, v8, 1.0
	v_fmac_f32_e32 v8, v9, v8
	v_div_scale_f32 v9, vcc, v6, v2, v6
	v_mul_f32_e32 v10, v9, v8
	v_fma_f32 v11, -v7, v10, v9
	v_fmac_f32_e32 v10, v11, v8
	v_fma_f32 v7, -v7, v10, v9
	v_div_fmas_f32 v7, v7, v8, v10
	v_div_fixup_f32 v2, v7, v2, v6
	v_pk_mul_f32 v[0:1], v[0:1], v[228:229]
	v_pk_mul_f32 v[34:35], v[34:35], v[228:229]
	v_pk_mul_f32 v[4:5], v[4:5], v[228:229]
	v_pk_mul_f32 v[2:3], v[2:3], v[228:229]

; __device__ __forceinline__ float bf2f(bf16_t h) { return __uint_as_float(((unsigned)h) << 16); }
; __device__ __forceinline__ void mlstm_local_unit(const Params& p, int layer, int uci, char* smem) {
;     ...
;     {
;         const float* cw = p.in[29] + (size_t)layer * 3 * 256; const float* cb = p.in[30] + (size_t)layer * 256;
;         const int lo = t < CTX ? 0 : CTX, hi = t < CTX ? CTX : TT;
;         const bool hp = t > lo, hn = t + 1 < hi;
;         const int c = 128 + h * 32 + part * 8;
;         const bf16x8 cur = *(const bf16x8*)(zr + c);
;         bf16x8 pv = cur, nx = cur;
;         if (hp) pv = *(const bf16x8*)(zr + c - 784);
;         if (hn) nx = *(const bf16x8*)(zr + c + 784);
;         const f32x4 w0a = *(const f32x4*)(cw + c), w0b = *(const f32x4*)(cw + c + 4), w1a = *(const f32x4*)(cw + 256 + c), w1b = *(const f32x4*)(cw + 256 + c + 4);
;         const f32x4 w2a = *(const f32x4*)(cw + 512 + c), w2b = *(const f32x4*)(cw + 512 + c + 4), bba = *(const f32x4*)(cb + c), bbb = *(const f32x4*)(cb + c + 4);
; #pragma unroll
;         for (int j = 0; j < 8; ++j) {
;             const float w0 = j < 4 ? w0a[j & 3] : w0b[j & 3], w1 = j < 4 ? w1a[j & 3] : w1b[j & 3], w2 = j < 4 ? w2a[j & 3] : w2b[j & 3], bb = j < 4 ? bba[j & 3] : bbb[j & 3];
;             float a = bf2f((bf16_t)cur[j]) * w1 + bb;
;             if (hp) a += bf2f((bf16_t)pv[j]) * w0;
;             if (hn) a += bf2f((bf16_t)nx[j]) * w2;
;             kv[j] = siluf_(a);
;         }
;         const bf16x8 v0 = *(const bf16x8*)(zr + 256 + h * 64 + part * 16), v1 = *(const bf16x8*)(zr + 256 + h * 64 + part * 16 + 8);
; #pragma unroll
;         for (int j = 0; j < 8; ++j) { *(bf16_t*)(smem + LV + (part * 16 + j) * 144 + s * 2) = (bf16_t)v0[j]; *(bf16_t*)(smem + LV + (part * 16 + 8 + j) * 144 + s * 2) = (bf16_t)v1[j]; }
;     }
;     __syncthreads();
;     if (wid == 0) {
;         float x = F[lane];
; #pragma unroll
;         for (int o = 1; o < 64; o <<= 1) { const float y = __shfl_up(x, o); if (lane >= o) x += y; }
;         float pm = F[64 + lane] - x;
;         const float aj = pm;
; #pragma unroll
;         for (int o = 1; o < 64; o <<= 1) { const float y = __shfl_up(pm, o); if (lane >= o) pm = fmaxf(pm, y); }
;         const float g = __shfl(x, 63), pm63 = __shfl(pm, 63);
;         F[128 + lane] = expf(aj - pm63);
;         if (lane == 0) { F[192] = g; F[193] = pm63; }
;     }
.LBB0_593:
	s_or_b64 exec, exec, s[0:1]
	s_lshl_b32 s0, s44, 5
	v_lshl_or_b32 v16, v45, 3, s0
	v_lshlrev_b32_e32 v104, 1, v16
	v_lshl_add_u64 v[14:15], v[12:13], 0, v[104:105]
	global_load_dwordx4 v[0:3], v[14:15], off offset:256
	s_movk_i32 s0, 0x100
	v_cmp_gt_i32_e64 s[0:1], s0, v8
	s_nop 1
	v_cndmask_b32_e64 v4, v205, 0, s[0:1]
	v_cmp_gt_i32_e32 vcc, v8, v4
	global_load_dwordx4 v[4:7], v[14:15], off offset:-1312
	v_cndmask_b32_e64 v9, v204, v205, s[0:1]
	v_add_u32_e32 v8, 1, v8
	v_cmp_lt_i32_e64 s[42:43], v8, v9
	global_load_dwordx4 v[8:11], v[14:15], off offset:1824
	s_lshl_b32 s0, s44, 7
	s_mov_b32 s1, s89
	v_lshl_add_u64 v[12:13], v[12:13], 0, s[0:1]
	v_lshlrev_b32_e32 v104, 5, v45
	v_readlane_b32 s0, v254, 44
	v_lshl_add_u64 v[12:13], v[12:13], 0, v[104:105]
	v_lshlrev_b32_e32 v40, 2, v16
	v_readlane_b32 s1, v254, 45
	global_load_dwordx4 v[50:53], v[12:13], off offset:512
	global_load_dwordx4 v[54:57], v[12:13], off offset:528
	s_nop 2
	global_load_dwordx4 v[12:15], v40, s[0:1] offset:528
	global_load_dwordx4 v[28:31], v40, s[0:1] offset:512
	global_load_dwordx4 v[20:23], v40, s[0:1] offset:1552
	global_load_dwordx4 v[36:39], v40, s[0:1] offset:1536
	global_load_dwordx4 v[16:19], v40, s[0:1] offset:2576
	global_load_dwordx4 v[32:35], v40, s[0:1] offset:2560
	v_readlane_b32 s0, v254, 46
	v_readlane_b32 s1, v254, 47
	s_nop 4
	global_load_dwordx4 v[24:27], v40, s[0:1] offset:528
	s_nop 0
	global_load_dwordx4 v[40:43], v40, s[0:1] offset:512
	v_lshlrev_b32_e32 v49, 1, v48
	v_mad_u32_u24 v46, v45, s33, v49
	v_cmp_gt_u32_e64 s[0:1], 64, v44
	s_waitcnt vmcnt(9)
	ds_write_b16 v46, v50 offset:4608
	s_waitcnt vmcnt(8)
	ds_write_b16 v46, v54 offset:5760
	ds_write_b16_d16_hi v46, v50 offset:4752
	ds_write_b16_d16_hi v46, v54 offset:5904
	ds_write_b16 v46, v51 offset:4896
	ds_write_b16 v46, v55 offset:6048
	ds_write_b16_d16_hi v46, v51 offset:5040
	ds_write_b16_d16_hi v46, v55 offset:6192
	ds_write_b16 v46, v52 offset:5184
	ds_write_b16 v46, v56 offset:6336
	ds_write_b16_d16_hi v46, v52 offset:5328
	ds_write_b16_d16_hi v46, v56 offset:6480
	ds_write_b16 v46, v53 offset:5472
	ds_write_b16 v46, v57 offset:6624
	ds_write_b16_d16_hi v46, v53 offset:5616
	ds_write_b16_d16_hi v46, v57 offset:6768
	s_waitcnt lgkmcnt(0)
	s_barrier
	s_and_saveexec_b64 s[34:35], s[0:1]
	s_cbranch_execz .LBB0_600
	v_and_b32_e32 v46, 63, v44
	v_lshlrev_b32_e32 v47, 2, v46
	ds_read_b32 v47, v47 offset:13824
	v_and_b32_e32 v50, 64, v195
	v_add_u32_e32 v51, -1, v195
	v_cmp_lt_i32_e64 s[0:1], v51, v50
	v_cmp_eq_u32_e64 s[44:45], 0, v46
	v_cmp_gt_u32_e64 s[46:47], 2, v46
	v_cndmask_b32_e64 v51, v51, v195, s[0:1]
	v_lshlrev_b32_e32 v51, 2, v51
	s_waitcnt lgkmcnt(0)
	ds_bpermute_b32 v52, v51, v47
	v_cmp_gt_u32_e64 s[48:49], 4, v46
	v_cmp_gt_u32_e64 s[50:51], 8, v46
	v_cmp_gt_u32_e64 s[52:53], 16, v46
	v_cmp_gt_u32_e64 s[54:55], 32, v46
	s_waitcnt lgkmcnt(0)
	v_add_f32_e32 v52, v47, v52
	v_cndmask_b32_e64 v47, v52, v47, s[44:45]
	v_add_u32_e32 v52, -2, v195
	v_cmp_lt_i32_e64 s[0:1], v52, v50
	s_nop 1
	v_cndmask_b32_e64 v52, v52, v195, s[0:1]
	v_lshlrev_b32_e32 v52, 2, v52
	ds_bpermute_b32 v53, v52, v47
	s_waitcnt lgkmcnt(0)
	v_add_f32_e32 v53, v47, v53
	v_cndmask_b32_e64 v47, v53, v47, s[46:47]
	v_add_u32_e32 v53, -4, v195
	v_cmp_lt_i32_e64 s[0:1], v53, v50
	s_nop 1
	v_cndmask_b32_e64 v53, v53, v195, s[0:1]
	v_lshlrev_b32_e32 v53, 2, v53
	ds_bpermute_b32 v54, v53, v47
	s_waitcnt lgkmcnt(0)
	v_add_f32_e32 v54, v47, v54
	v_cndmask_b32_e64 v47, v54, v47, s[48:49]
	v_add_u32_e32 v54, -8, v195
	v_cmp_lt_i32_e64 s[0:1], v54, v50
	s_nop 1
	v_cndmask_b32_e64 v54, v54, v195, s[0:1]
	v_lshlrev_b32_e32 v54, 2, v54
	ds_bpermute_b32 v55, v54, v47
	s_waitcnt lgkmcnt(0)
	v_add_f32_e32 v55, v47, v55
	v_cndmask_b32_e64 v47, v55, v47, s[50:51]
	v_add_u32_e32 v55, -16, v195
	v_cmp_lt_i32_e64 s[0:1], v55, v50
	s_nop 1
	v_cndmask_b32_e64 v55, v55, v195, s[0:1]
	v_lshlrev_b32_e32 v55, 2, v55
	ds_bpermute_b32 v56, v55, v47
	s_waitcnt lgkmcnt(0)
	v_add_f32_e32 v56, v47, v56
	v_cndmask_b32_e64 v47, v56, v47, s[52:53]
	v_subrev_u32_e32 v56, 32, v195
	v_cmp_lt_i32_e64 s[0:1], v56, v50
	s_nop 1
	v_cndmask_b32_e64 v50, v56, v195, s[0:1]
	v_lshlrev_b32_e32 v50, 2, v50
	ds_bpermute_b32 v56, v50, v47
	s_waitcnt lgkmcnt(0)
	v_add_f32_e32 v46, v47, v56
	v_lshlrev_b32_e32 v56, 2, v44
	v_cndmask_b32_e64 v46, v46, v47, s[54:55]
	ds_read_b32 v47, v56 offset:14080
	s_waitcnt lgkmcnt(0)
	v_sub_f32_e32 v57, v47, v46
	ds_bpermute_b32 v47, v51, v57
	s_waitcnt lgkmcnt(0)
	v_max_f32_e32 v47, v47, v47
	v_max_f32_e32 v47, v57, v47
	v_cndmask_b32_e64 v47, v47, v57, s[44:45]
	ds_bpermute_b32 v51, v52, v47
	s_waitcnt lgkmcnt(0)
	v_max_f32_e32 v51, v51, v51
	v_max_f32_e32 v51, v47, v51
	v_cndmask_b32_e64 v47, v51, v47, s[46:47]
	ds_bpermute_b32 v51, v53, v47
	s_waitcnt lgkmcnt(0)
	v_max_f32_e32 v51, v51, v51
	v_max_f32_e32 v51, v47, v51
	v_cndmask_b32_e64 v47, v51, v47, s[48:49]
	ds_bpermute_b32 v51, v54, v47
	s_waitcnt lgkmcnt(0)
	v_max_f32_e32 v51, v51, v51
	v_max_f32_e32 v51, v47, v51
	v_cndmask_b32_e64 v47, v51, v47, s[50:51]
	ds_bpermute_b32 v51, v55, v47
	s_waitcnt lgkmcnt(0)
	v_max_f32_e32 v51, v51, v51
	v_max_f32_e32 v51, v47, v51
	v_cndmask_b32_e64 v47, v51, v47, s[52:53]
	ds_bpermute_b32 v50, v50, v47
	v_max_f32_e32 v51, v47, v47
	s_waitcnt lgkmcnt(0)
	v_max_f32_e32 v50, v50, v50
	v_max_f32_e32 v50, v51, v50
	v_cndmask_b32_e64 v47, v50, v47, s[54:55]
	v_lshl_or_b32 v50, v195, 2, v207
	ds_bpermute_b32 v47, v50, v47
	ds_bpermute_b32 v46, v50, v46
	s_waitcnt lgkmcnt(1)
	v_sub_f32_e32 v50, v57, v47
	v_mul_f32_e32 v51, 0x3fb8aa3b, v50
	v_fma_f32 v52, v50, s37, -v51
	v_rndne_f32_e32 v53, v51
	v_fmac_f32_e32 v52, 0x32a5705f, v50
	v_sub_f32_e32 v51, v51, v53
	v_add_f32_e32 v51, v51, v52
	v_exp_f32_e32 v51, v51
	v_cvt_i32_f32_e32 v52, v53
	v_cmp_ngt_f32_e64 s[0:1], s38, v50
	v_ldexp_f32 v51, v51, v52
	s_nop 0
	v_cndmask_b32_e64 v51, 0, v51, s[0:1]
	v_cmp_nlt_f32_e64 s[0:1], s39, v50
	s_nop 1
	v_cndmask_b32_e64 v50, v202, v51, s[0:1]
	ds_write_b32 v56, v50 offset:14336
	s_and_b64 exec, exec, s[44:45]
	s_cbranch_execz .LBB0_600
	s_waitcnt lgkmcnt(1)
	ds_write_b64 v105, v[46:47] offset:14592
